# stack11 + first K fragment LDS read issued ahead of the partner P-fragment reads at each step top
# speedup vs baseline: 1.0245x; 1.0011x over previous
.LBB0_734:
	v_add_u32_e32 v167, s79, v147
	ds_read_b128 v[64:67], v167
	v_add_u32_e32 v128, s78, v145
	ds_read_b128 v[124:127], v128 offset:1024
	ds_read_b128 v[120:123], v128
	ds_read_b32 v166, v156 offset:8192
	s_add_i32 s54, s19, -2
	s_cmp_lt_i32 s54, s18
	s_cselect_b64 s[52:53], -1, 0
	s_cmp_ge_i32 s54, s18
	v_lshl_add_u64 v[134:135], s[50:51], 0, v[132:133]
	s_cbranch_scc1 .LBB0_738
.Li0_entry:
	v_add_u32_e32 v227, s79, v149
	v_add_u32_e32 v194, s79, v151
	v_add_u32_e32 v195, s79, v153
	ds_read_b128 v[188:191], v227
	ds_read_b128 v[228:231], v194
	s_waitcnt lgkmcnt(5)
	v_mfma_f32_32x32x16_bf16 v[64:79], v[64:67], v[80:83], 0
	s_waitcnt lgkmcnt(1)
	v_mfma_f32_32x32x16_bf16 v[64:79], v[188:191], v[84:87], v[64:79]
	ds_read_b128 v[188:191], v195
	s_mov_b64 s[54:55], 0xe404000
	s_add_i32 m0, s96, 0x8000
	v_lshl_add_u64 v[192:193], v[134:135], 0, s[54:55]
	s_nop 0
	global_load_lds_dwordx4 v[192:193], off
	v_cndmask_b32_e64 v173, v113, v121, s[2:3]
	v_cndmask_b32_e64 v172, v112, v120, s[2:3]
	v_cndmask_b32_e64 v177, v121, v113, s[2:3]
	v_cndmask_b32_e64 v176, v120, v112, s[2:3]
	s_waitcnt lgkmcnt(1)
	v_mfma_f32_32x32x16_bf16 v[64:79], v[228:231], v[88:91], v[64:79]
	ds_read_b128 v[228:231], v167 offset:128
	s_mov_b64 s[54:55], 0xe406000
	s_add_i32 m0, s96, 0xa000
	v_lshl_add_u64 v[192:193], v[134:135], 0, s[54:55]
	s_nop 0
	global_load_lds_dwordx4 v[192:193], off
	v_cndmask_b32_e64 v171, v119, v127, s[2:3]
	v_cndmask_b32_e64 v170, v118, v126, s[2:3]
	v_cndmask_b32_e64 v169, v117, v125, s[2:3]
	v_cndmask_b32_e64 v168, v116, v124, s[2:3]
	s_waitcnt lgkmcnt(1)
	v_mfma_f32_32x32x16_bf16 v[64:79], v[188:191], v[92:95], v[64:79]
	ds_read_b128 v[188:191], v227 offset:128
	s_mov_b64 s[54:55], 0xe804000
	s_add_i32 m0, s96, 0xc000
	v_lshl_add_u64 v[192:193], v[134:135], 0, s[54:55]
	s_nop 0
	global_load_lds_dwordx4 v[192:193], off
	v_cndmask_b32_e64 v175, v115, v123, s[2:3]
	v_cndmask_b32_e64 v174, v114, v122, s[2:3]
	v_cndmask_b32_e64 v127, v127, v119, s[2:3]
	v_cndmask_b32_e64 v126, v126, v118, s[2:3]
	s_waitcnt lgkmcnt(1)
	v_mfma_f32_32x32x16_bf16 v[64:79], v[228:231], v[96:99], v[64:79]
	ds_read_b128 v[228:231], v194 offset:128
	s_mov_b64 s[54:55], 0xe806000
	s_add_i32 m0, s96, 0xe000
	v_lshl_add_u64 v[192:193], v[134:135], 0, s[54:55]
	s_nop 0
	global_load_lds_dwordx4 v[192:193], off
	v_cndmask_b32_e64 v125, v125, v117, s[2:3]
	v_cndmask_b32_e64 v124, v124, v116, s[2:3]
	v_cndmask_b32_e64 v179, v123, v115, s[2:3]
	v_cndmask_b32_e64 v178, v122, v114, s[2:3]
	s_waitcnt lgkmcnt(1)
	v_mfma_f32_32x32x16_bf16 v[64:79], v[188:191], v[100:103], v[64:79]
	ds_read_b128 v[188:191], v195 offset:128
	s_cmp_gt_i32 s19, s18
	s_cbranch_scc1 .Li0_kskip
	v_lshl_add_u64 v[192:193], s[50:51], 0, v[130:131]
	s_mov_b64 s[54:55], 0xc408000
	s_mov_b32 m0, s97
	v_lshl_add_u64 v[192:193], v[192:193], 0, s[54:55]
	s_nop 0
	global_load_lds_dwordx4 v[192:193], off
	v_lshl_add_u64 v[192:193], s[50:51], 0, v[130:131]
	s_mov_b64 s[54:55], 0xc40a000
	s_mov_b32 m0, s26
	v_lshl_add_u64 v[192:193], v[192:193], 0, s[54:55]
	s_nop 0
	global_load_lds_dwordx4 v[192:193], off

.LBB0_748:
	ds_read_b128 v[64:67], v148
	ds_read_b128 v[124:127], v128 offset:5120
	ds_read_b128 v[120:123], v128 offset:4096
	ds_read_b32 v128, v156 offset:8448
	s_cmp_gt_i32 s19, s18
	s_cselect_b64 s[52:53], -1, 0
	s_cmp_le_i32 s19, s18
	s_cselect_b64 s[54:55], -1, 0
	s_and_b64 vcc, exec, s[52:53]
	s_cbranch_vccnz .LBB0_752
.Li1_entry:
	ds_read_b128 v[188:191], v150
	ds_read_b128 v[228:231], v152
	s_waitcnt lgkmcnt(5)
	v_mfma_f32_32x32x16_bf16 v[64:79], v[64:67], v[80:83], 0
	s_waitcnt lgkmcnt(1)
	v_mfma_f32_32x32x16_bf16 v[64:79], v[188:191], v[84:87], v[64:79]
	ds_read_b128 v[188:191], v154
	s_mov_b64 s[56:57], 0xe408000
	s_mov_b32 m0, s96
	v_lshl_add_u64 v[192:193], v[134:135], 0, s[56:57]
	s_nop 0
	global_load_lds_dwordx4 v[192:193], off
	v_cndmask_b32_e64 v173, v113, v121, s[2:3]
	v_cndmask_b32_e64 v172, v112, v120, s[2:3]
	v_cndmask_b32_e64 v177, v121, v113, s[2:3]
	v_cndmask_b32_e64 v176, v120, v112, s[2:3]
	s_waitcnt lgkmcnt(1)
	v_mfma_f32_32x32x16_bf16 v[64:79], v[228:231], v[88:91], v[64:79]
	ds_read_b128 v[228:231], v148 offset:128
	s_mov_b64 s[56:57], 0xe40a000
	s_mov_b32 m0, s6
	v_lshl_add_u64 v[192:193], v[134:135], 0, s[56:57]
	s_nop 0
	global_load_lds_dwordx4 v[192:193], off
	v_cndmask_b32_e64 v171, v127, v119, s[2:3]
	v_cndmask_b32_e64 v170, v126, v118, s[2:3]
	v_cndmask_b32_e64 v169, v125, v117, s[2:3]
	v_cndmask_b32_e64 v168, v124, v116, s[2:3]
	s_waitcnt lgkmcnt(1)
	v_mfma_f32_32x32x16_bf16 v[64:79], v[188:191], v[92:95], v[64:79]
	ds_read_b128 v[188:191], v150 offset:128
	s_mov_b64 s[56:57], 0xe808000
	s_mov_b32 m0, s7
	v_lshl_add_u64 v[192:193], v[134:135], 0, s[56:57]
	s_nop 0
	global_load_lds_dwordx4 v[192:193], off
	v_cndmask_b32_e64 v175, v115, v123, s[2:3]
	v_cndmask_b32_e64 v174, v114, v122, s[2:3]
	v_cndmask_b32_e64 v127, v119, v127, s[2:3]
	v_cndmask_b32_e64 v126, v118, v126, s[2:3]
	s_waitcnt lgkmcnt(1)
	v_mfma_f32_32x32x16_bf16 v[64:79], v[228:231], v[96:99], v[64:79]
	ds_read_b128 v[228:231], v152 offset:128
	s_mov_b64 s[56:57], 0xe80a000
	s_mov_b32 m0, s24
	v_lshl_add_u64 v[192:193], v[134:135], 0, s[56:57]
	s_nop 0
	global_load_lds_dwordx4 v[192:193], off
	v_cndmask_b32_e64 v125, v117, v125, s[2:3]
	v_cndmask_b32_e64 v124, v116, v124, s[2:3]
	v_cndmask_b32_e64 v179, v123, v115, s[2:3]
	v_cndmask_b32_e64 v178, v122, v114, s[2:3]
	s_waitcnt lgkmcnt(1)
	v_mfma_f32_32x32x16_bf16 v[64:79], v[188:191], v[100:103], v[64:79]
	ds_read_b128 v[188:191], v154 offset:128
	s_add_i32 s56, s19, 1
	s_cmp_gt_i32 s56, s18
	s_cbranch_scc1 .Li1_kskip
	v_lshl_add_u64 v[192:193], s[50:51], 0, v[130:131]
	s_mov_b64 s[56:57], 0xc40c000
	s_mov_b32 m0, s27
	v_lshl_add_u64 v[192:193], v[192:193], 0, s[56:57]
	s_nop 0
	global_load_lds_dwordx4 v[192:193], off
	v_lshl_add_u64 v[192:193], s[50:51], 0, v[130:131]
	s_mov_b64 s[56:57], 0xc40e000
	s_mov_b32 m0, s62
	v_lshl_add_u64 v[192:193], v[192:193], 0, s[56:57]
	s_nop 0
	global_load_lds_dwordx4 v[192:193], off
